# GDN chain: second barrier of a chunk placed after the issue of the next chunk's global loads (address math overlaps the LDS write drain)
# baseline (speedup 1.0000x reference)
; #define LAS __attribute__((address_space(3)))
; __device__ __forceinline__ bf16_t f2bf(float f) { return (bf16_t)(pk2(f, f) & 0xFFFFu); }
; template <int MODE>
; __device__ NOINL void chain_item(const LAS Params* lp, int l, int item, bool ctx_out, LAS unsigned char* lds) {
;     ...
;     auto issue = [&](int n) {
;         const int cid = n < 4 ? (dir ? 3 - n : n) : (dir ? 39 - n : n);
;         int row0, t0, L; chunk_geom(b, cid, row0, t0, L);
;         const bf16_t* src = p.proj + (size_t)(row0 + tk) * 3072 + lcol;
;         rq[0] = *(const u32x4*)src; rq[1] = *(const u32x4*)(src + 8);
;         rk[0] = *(const u32x4*)(src + lstep); rk[1] = *(const u32x4*)(src + lstep + 8);
;         rv[0] = *(const u32x4*)(src + 2 * lstep); rv[1] = *(const u32x4*)(src + 2 * lstep + 8);
;         if (MODE == 0) {
;             rt = *(const u32x4*)(p.Tbuf + ((((size_t)b * 4 + h) * 36 + cid) * 2 + dir) * 4096 + tid * 8);
;             if (tid < 192) rg = p.gcbuf[((((size_t)b * 4 + h) * 36 + cid) * 2 + dir) * 192 + tid];
;         }
;     };
;     issue(0);
;     for (int n = 0; n < 36; ++n) {
;         const int cid = n < 4 ? (dir ? 3 - n : n) : (dir ? 39 - n : n);
;         int row0, t0, L; chunk_geom(b, cid, row0, t0, L);
;         __syncthreads();
;         u32x4 kk0 = rk[0], kk1 = rk[1];
;         *(LAS u32x4*)(Qs + pp * 136 + lrow) = rq[0]; *(LAS u32x4*)(Qs + pp * 136 + lrow + 8) = rq[1];
;         *(LAS u32x4*)(Ks + pp * 136 + lrow) = kk0; *(LAS u32x4*)(Ks + pp * 136 + lrow + 8) = kk1;
;         {
;             const unsigned vv[8] = {rv[0].x, rv[0].y, rv[0].z, rv[0].w, rv[1].x, rv[1].y, rv[1].z, rv[1].w};
; #pragma unroll
;             for (int e = 0; e < 8; ++e) { VT[(lrow + 2 * e) * 72 + ppz] = (bf16_t)(vv[e] & 0xFFFFu); VT[(lrow + 2 * e + 1) * 72 + ppz] = (bf16_t)(vv[e] >> 16); }
;         }
;         if (MODE == 0) {
;             *(LAS u32x4*)(TT + (tid >> 3) * 72 + (tid & 7) * 8) = rt;
;             if (tid < 192) gcs[tid] = rg;
;         } else {
;             const float ksc = __expf((float)(63 - pp) * lgl);
;             float kf[16]; unpack8(kk0, kf); unpack8(kk1, kf + 8);
; #pragma unroll
;             for (int e = 0; e < 16; ++e) KT[(lrow + e) * 72 + ppz] = f2bf(kf[e] * ksc);
;         }
;         __syncthreads();
;         if (n + 1 < 36) issue(n + 1);
.LBB0_1142:
	s_barrier
	s_waitcnt vmcnt(5)
	ds_write_b128 v151, v[12:15]
	ds_write_b128 v151, v[8:11] offset:16
	s_waitcnt vmcnt(3)
	ds_write_b128 v151, v[72:75] offset:17408
	ds_write_b128 v151, v[68:71] offset:17424
	s_waitcnt vmcnt(1)
	ds_write_b16 v163, v20 offset:53248
	ds_write_b16_d16_hi v163, v20 offset:53392
	ds_write_b16 v163, v21 offset:53536
	ds_write_b16_d16_hi v163, v21 offset:53680
	ds_write_b16 v163, v22 offset:53824
	ds_write_b16_d16_hi v163, v22 offset:53968
	ds_write_b16 v163, v23 offset:54112
	ds_write_b16_d16_hi v163, v23 offset:54256
	ds_write_b16 v163, v16 offset:54400
	ds_write_b16_d16_hi v163, v16 offset:54544
	ds_write_b16 v163, v17 offset:54688
	ds_write_b16_d16_hi v163, v17 offset:54832
	ds_write_b16 v163, v18 offset:54976
	ds_write_b16_d16_hi v163, v18 offset:55120
	ds_write_b16 v163, v19 offset:55264
	ds_write_b16_d16_hi v163, v19 offset:55408
	s_waitcnt vmcnt(0)
	ds_write_b128 v152, v[24:27]
	s_and_saveexec_b64 s[62:63], s[44:45]
	ds_write_b32 v156, v150
	s_or_b64 exec, exec, s[62:63]
	s_add_i32 s0, s1, 1
	s_cmp_eq_u32 s1, 35
	s_cbranch_scc1 .LBB0_1148
	s_cmp_lt_u32 s1, 3
	s_cselect_b32 s5, 3, 39
	s_add_i32 s5, s5, s4
	s_and_b64 s[20:21], vcc, exec
	s_cselect_b32 s5, s0, s5
	s_cmp_lt_i32 s5, 4
	s_cselect_b32 s20, 8, 11
	s_cselect_b32 s21, 0x8000, s14
	s_lshl_b32 s20, s29, s20
	s_lshl_b32 s22, s5, 6
	s_add_i32 s20, s20, s21
	s_add_i32 s20, s20, s22
	v_add_u32_e32 v8, s20, v111
	v_mad_i64_i32 v[20:21], s[20:21], v8, s81, v[2:3]
	s_ashr_i32 s20, s5, 31
	global_load_dwordx4 v[8:11], v[20:21], off offset:16
	global_load_dwordx4 v[12:15], v[20:21], off
	global_load_dwordx4 v[60:63], v[20:21], off offset:1040
	global_load_dwordx4 v[64:67], v[20:21], off offset:1024
	global_load_dwordx4 v[16:19], v[20:21], off offset:2064
	s_nop 0
	global_load_dwordx4 v[20:23], v[20:21], off offset:2048
	s_add_u32 s64, s39, s5
	s_addc_u32 s65, s41, s20
	s_lshl_b64 s[20:21], s[64:65], 14
	v_lshl_add_u64 v[24:25], v[108:109], 0, s[20:21]
	global_load_dwordx4 v[24:27], v[24:25], off
	s_and_saveexec_b64 s[62:63], s[44:45]
	s_cbranch_execz .LBB0_1147
	s_lshl_b64 s[20:21], s[64:65], 1
	s_or_b32 s5, s20, s27
	s_mul_i32 s22, s21, 0x300
	v_mad_u64_u32 v[76:77], s[20:21], s5, v229, v[114:115]
	v_add_u32_e32 v77, s22, v77
	global_load_dword v150, v[76:77], off

; #define LAS __attribute__((address_space(3)))
; __device__ __forceinline__ bf16_t f2bf(float f) { return (bf16_t)(pk2(f, f) & 0xFFFFu); }
; #define MFMA16(a, b, c) __builtin_amdgcn_mfma_f32_16x16x32_bf16((a), (b), (c), 0, 0, 0)
; template <int MODE>
; __device__ NOINL void chain_item(const LAS Params* lp, int l, int item, bool ctx_out, LAS unsigned char* lds) {
;     ...
;         __syncthreads();
;         if (n + 1 < 36) issue(n + 1);
;         if (MODE == 0) {
;             const float sc = __expf(gcs[63] - gcs[pp]);
;             {
;                 float kf[16]; unpack8(kk0, kf); unpack8(kk1, kf + 8);
; #pragma unroll
;                 for (int e = 0; e < 16; ++e) KT[(lrow + e) * 72 + ppz] = f2bf(kf[e] * sc);
;             }
;             const int ct = w >> 1;
; #pragma unroll
;             for (int jj = 0; jj < 2; ++jj) {
;                 const int st = 2 * (w & 1) + jj; f32x4 acc = {0.f, 0.f, 0.f, 0.f};
; #pragma unroll
;                 for (int ks = 0; ks < 4; ++ks) {
;                     const bf16x8 A = *(const LAS bf16x8*)(Qs + (16 * ct + fr) * 136 + ks * 32 + fq * 8), B = *(const LAS bf16x8*)(Ks + (16 * st + fr) * 136 + ks * 32 + fq * 8);
;                     acc = MFMA16(A, B, acc);
;                 }
;                 const int s = 16 * st + fr; const float gs = gcs[s];
; #pragma unroll
;                 for (int j = 0; j < 4; ++j) { const int c = 16 * ct + 4 * fq + j; AT[c * 72 + s] = f2bf(s <= c ? acc[j] * __expf(gcs[c] - gs) : 0.f); }
;             }
.LBB0_1149:
	s_waitcnt lgkmcnt(0)
	s_barrier
	v_mov_b32_e32 v76, s16
	ds_read_b32 v76, v76
	ds_read_b32 v77, v153
	ds_read_b128 v[88:91], v112
	ds_read_b128 v[92:95], v112 offset:64
	ds_read_b128 v[96:99], v112 offset:128
	ds_read_b128 v[100:103], v112 offset:192
	ds_read_b128 v[104:107], v192 offset:17408
	ds_read_b128 v[194:197], v192 offset:17472
	ds_read_b128 v[198:201], v192 offset:17536
	ds_read_b128 v[232:235], v192 offset:17600
	ds_read_b32 v85, v164
	ds_read_b32 v86, v174
	ds_read_b32 v87, v166
	ds_read_b32 v148, v168
	ds_read_b32 v149, v170
	ds_read_b32 v193, v172
	v_lshlrev_b32_e32 v78, 16, v73
	v_lshlrev_b32_e32 v81, 16, v68
	v_and_b32_e32 v68, 0xffff0000, v68
	v_and_b32_e32 v73, 0xffff0000, v73
	s_waitcnt lgkmcnt(14)
	v_sub_f32_e32 v76, v76, v77
	v_mul_f32_e32 v76, 0x3fb8aa3b, v76
	v_exp_f32_e32 v76, v76
	v_lshlrev_b32_e32 v77, 16, v72
	v_and_b32_e32 v72, 0xffff0000, v72
	v_lshlrev_b32_e32 v82, 16, v69
	v_mul_f32_e32 v72, v76, v72
	v_cvt_pk_bf16_f32 v72, v72, s0
	ds_write_b16 v185, v72 offset:34960
	v_mul_f32_e32 v72, v76, v78
	v_mul_f32_e32 v68, v76, v68
	v_cvt_pk_bf16_f32 v72, v72, s0
	v_cvt_pk_bf16_f32 v68, v68, s0
	ds_write_b16 v185, v72 offset:35104
	v_mul_f32_e32 v72, v76, v73
	ds_write_b16 v185, v68 offset:36112
	v_mul_f32_e32 v68, v76, v82
	v_lshlrev_b32_e32 v79, 16, v74
	v_and_b32_e32 v69, 0xffff0000, v69
	v_cvt_pk_bf16_f32 v72, v72, s0
	v_cvt_pk_bf16_f32 v68, v68, s0
	ds_write_b16 v185, v72 offset:35248
	v_mul_f32_e32 v72, v76, v79
	ds_write_b16 v185, v68 offset:36256
	v_mul_f32_e32 v68, v76, v69
	v_and_b32_e32 v74, 0xffff0000, v74
	v_lshlrev_b32_e32 v83, 16, v70
	v_cvt_pk_bf16_f32 v72, v72, s0
	v_cvt_pk_bf16_f32 v68, v68, s0
	ds_write_b16 v185, v72 offset:35392
	v_mul_f32_e32 v72, v76, v74
	ds_write_b16 v185, v68 offset:36400
	v_mul_f32_e32 v68, v76, v83
	v_lshlrev_b32_e32 v80, 16, v75
	v_and_b32_e32 v70, 0xffff0000, v70
	v_cvt_pk_bf16_f32 v72, v72, s0
	v_cvt_pk_bf16_f32 v68, v68, s0
	ds_write_b16 v185, v72 offset:35536
	v_mul_f32_e32 v72, v76, v80
	ds_write_b16 v185, v68 offset:36544
	v_mul_f32_e32 v68, v76, v70
	v_and_b32_e32 v75, 0xffff0000, v75
	v_lshlrev_b32_e32 v84, 16, v71
	v_cvt_pk_bf16_f32 v72, v72, s0
	v_cvt_pk_bf16_f32 v68, v68, s0
	ds_write_b16 v185, v72 offset:35680
	v_mul_f32_e32 v72, v76, v75
	ds_write_b16 v185, v68 offset:36688
	v_mul_f32_e32 v68, v76, v84
	v_and_b32_e32 v71, 0xffff0000, v71
	v_cvt_pk_bf16_f32 v72, v72, s0
	v_cvt_pk_bf16_f32 v68, v68, s0
	v_mul_f32_e32 v77, v76, v77
	ds_write_b16 v185, v72 offset:35824
	v_mul_f32_e32 v72, v76, v81
	ds_write_b16 v185, v68 offset:36832
	v_mul_f32_e32 v68, v76, v71
	v_cvt_pk_bf16_f32 v77, v77, s0
	v_cvt_pk_bf16_f32 v72, v72, s0
	v_cvt_pk_bf16_f32 v68, v68, s0
	ds_write_b16 v185, v77 offset:34816
	ds_write_b16 v185, v72 offset:35968
	ds_write_b16 v185, v68 offset:36976
	ds_read_b128 v[236:239], v192 offset:21760
	ds_read_b128 v[240:243], v192 offset:21824
	ds_read_b128 v[244:247], v192 offset:21888
	ds_read_b128 v[248:251], v192 offset:21952
	s_waitcnt lgkmcnt(14)
	v_mfma_f32_16x16x32_bf16 v[68:71], v[88:91], v[104:107], 0
	v_mfma_f32_16x16x32_bf16 v[68:71], v[92:95], v[194:197], v[68:71]
	v_mfma_f32_16x16x32_bf16 v[68:71], v[96:99], v[198:201], v[68:71]
	v_mfma_f32_16x16x32_bf16 v[68:71], v[100:103], v[232:235], v[68:71]
	s_waitcnt lgkmcnt(3)
	v_mfma_f32_16x16x32_bf16 v[72:75], v[88:91], v[236:239], 0
	s_waitcnt lgkmcnt(2)
	v_mfma_f32_16x16x32_bf16 v[72:75], v[92:95], v[240:243], v[72:75]
	s_waitcnt lgkmcnt(1)
	v_mfma_f32_16x16x32_bf16 v[72:75], v[96:99], v[244:247], v[72:75]
	s_waitcnt lgkmcnt(0)
	v_mfma_f32_16x16x32_bf16 v[72:75], v[100:103], v[248:251], v[72:75]
	v_sub_f32_e32 v76, v87, v85
	v_sub_f32_e32 v77, v148, v85
	v_sub_f32_e32 v78, v149, v85
	v_sub_f32_e32 v79, v193, v85
	v_sub_f32_e32 v80, v87, v86
	v_sub_f32_e32 v81, v148, v86
	v_sub_f32_e32 v82, v149, v86
	v_sub_f32_e32 v83, v193, v86
	v_mul_f32_e32 v76, 0x3fb8aa3b, v76
	v_mul_f32_e32 v77, 0x3fb8aa3b, v77
	v_mul_f32_e32 v78, 0x3fb8aa3b, v78
	v_mul_f32_e32 v79, 0x3fb8aa3b, v79
	v_mul_f32_e32 v80, 0x3fb8aa3b, v80
	v_mul_f32_e32 v81, 0x3fb8aa3b, v81
	v_mul_f32_e32 v82, 0x3fb8aa3b, v82
	v_mul_f32_e32 v83, 0x3fb8aa3b, v83
	v_exp_f32_e32 v76, v76
	v_exp_f32_e32 v77, v77
	v_exp_f32_e32 v78, v78
	v_exp_f32_e32 v79, v79
	v_exp_f32_e32 v80, v80
	v_exp_f32_e32 v81, v81
	v_exp_f32_e32 v82, v82
	v_exp_f32_e32 v83, v83
	v_add_u32_e32 v88, v165, v167
	v_add_u32_e32 v89, v165, v169
	v_add_u32_e32 v90, v165, v171
	v_add_u32_e32 v91, v165, v173
	v_mul_f32_e32 v76, v68, v76
	v_mul_f32_e32 v77, v69, v77
	v_mul_f32_e32 v78, v70, v78
	v_mul_f32_e32 v79, v71, v79
	v_mul_f32_e32 v80, v72, v80
	v_mul_f32_e32 v81, v73, v81
	v_mul_f32_e32 v82, v74, v82
	v_mul_f32_e32 v83, v75, v83
	v_cvt_pk_bf16_f32 v76, v76, v76
	v_cvt_pk_bf16_f32 v77, v77, v77
	v_cvt_pk_bf16_f32 v78, v78, v78
	v_cvt_pk_bf16_f32 v79, v79, v79
	v_cvt_pk_bf16_f32 v80, v80, v80
	v_cvt_pk_bf16_f32 v81, v81, v81
	v_cvt_pk_bf16_f32 v82, v82, v82
	v_cvt_pk_bf16_f32 v83, v83, v83
	v_cndmask_b32_e64 v76, 0, v76, s[46:47]
	v_cndmask_b32_e64 v77, 0, v77, s[48:49]
	v_cndmask_b32_e64 v78, 0, v78, s[50:51]
	v_cndmask_b32_e64 v79, 0, v79, s[52:53]
	v_cndmask_b32_e64 v80, 0, v80, s[54:55]
	v_cndmask_b32_e64 v81, 0, v81, s[56:57]
	v_cndmask_b32_e64 v82, 0, v82, s[58:59]
	v_cndmask_b32_e64 v68, 0, v83, s[60:61]
	ds_write_b16 v88, v76
	ds_write_b16 v89, v77
	ds_write_b16 v90, v78
	ds_write_b16 v91, v79
	ds_write_b16 v175, v80
	ds_write_b16 v176, v81
	ds_write_b16 v177, v82
	s_branch .LBB0_1141
